# prologue ada GEMV inner loop rewritten by hand: the 8 weight-row loads of a K-step issued together with one wait (was 4-5 serialized round trips per step)
# speedup vs baseline: 1.0072x; 1.0051x over previous
; __device__ __forceinline__ void phase_prologue(const KArgs& A, LAS unsigned char* lds, int wave, int lane) {
;     ...
;     for (int task = gw; task < 4 * 24 * ADA_SPLIT; task += NGW) {
;         const int l = task / (24 * ADA_SPLIT), rem = task % (24 * ADA_SPLIT), cgp = rem / ADA_SPLIT, s = rem % ADA_SPLIT;
;         constexpr int KS = 2048 / ADA_SPLIT;
;         const float* W = PICK4(l, A.in[4], A.in[15], A.in[23], A.in[33]) + (size_t)(s * KS) * 6144 + cgp * 256 + lane * 4;
;         f32x4 acc[9];
; #pragma unroll
;         for (int v = 0; v < 9; ++v) acc[v] = (f32x4){0.f, 0.f, 0.f, 0.f};
;         for (int k0 = 0; k0 < KS; k0 += 8) {
;             f32x4 w[8];
; #pragma unroll
;             for (int i = 0; i < 8; ++i) w[i] = *(const f32x4*)(W + (size_t)(k0 + i) * 6144);
; #pragma unroll
;             for (int i = 0; i < 8; ++i)
; #pragma unroll
;                 for (int v = 0; v < 9; ++v) acc[v] += w[i] * sl[v * 2048 + s * KS + k0 + i];
.LBB0_392:
	s_mul_hi_i32 s8, s2, 0x2aaaaaab
	s_lshr_b32 s9, s8, 31
	s_ashr_i32 s8, s8, 6
	s_add_i32 s8, s8, s9
	s_mul_i32 s9, s8, 0x180
	s_sub_i32 s9, s2, s9
	s_sext_i32_i16 s10, s9
	s_bfe_u32 s10, s10, 0x4001b
	s_add_i32 s10, s9, s10
	s_sext_i32_i16 s11, s10
	s_and_b32 s10, s10, 0xfff0
	s_load_dwordx2 s[12:13], s[6:7], 0x0
	s_sub_i32 s9, s9, s10
	s_sext_i32_i16 s9, s9
	s_lshl_b32 s6, s11, 4
	s_mul_i32 s16, s9, 0xc0000
	s_and_b32 s6, s6, 0xffffff00
	s_lshl_b32 s10, s9, 9
	s_ashr_i32 s17, s16, 31
	s_ashr_i32 s7, s6, 31
	s_add_i32 s10, s10, 0
	s_add_i32 s10, s10, 0x10000
	s_waitcnt lgkmcnt(0)
	v_lshl_add_u64 v[2:3], s[12:13], 0, v[0:1]
	s_lshl_b64 s[12:13], s[16:17], 2
	s_lshl_b64 s[16:17], s[6:7], 2
	s_add_u32 s12, s12, s16
	s_addc_u32 s13, s13, s17
	v_mov_b32_e32 v38, 0
	v_lshl_add_u64 v[48:49], v[2:3], 0, s[12:13]
	s_mov_b32 s11, -8
	v_mov_b32_e32 v39, v38
	v_mov_b32_e32 v40, v38
	v_mov_b32_e32 v41, v38
	v_mov_b32_e32 v42, v38
	v_mov_b32_e32 v43, v38
	v_mov_b32_e32 v44, v38
	v_mov_b32_e32 v45, v38
	v_mov_b32_e32 v34, v38
	v_mov_b32_e32 v35, v38
	v_mov_b32_e32 v36, v38
	v_mov_b32_e32 v37, v38
	v_mov_b32_e32 v30, v38
	v_mov_b32_e32 v31, v38
	v_mov_b32_e32 v32, v38
	v_mov_b32_e32 v33, v38
	v_mov_b32_e32 v26, v38
	v_mov_b32_e32 v27, v38
	v_mov_b32_e32 v28, v38
	v_mov_b32_e32 v29, v38
	v_mov_b32_e32 v14, v38
	v_mov_b32_e32 v15, v38
	v_mov_b32_e32 v16, v38
	v_mov_b32_e32 v17, v38
	v_mov_b32_e32 v22, v38
	v_mov_b32_e32 v23, v38
	v_mov_b32_e32 v24, v38
	v_mov_b32_e32 v25, v38
	v_mov_b32_e32 v2, v38
	v_mov_b32_e32 v3, v38
	v_mov_b32_e32 v4, v38
	v_mov_b32_e32 v5, v38
	v_mov_b32_e32 v6, v38
	v_mov_b32_e32 v7, v38
	v_mov_b32_e32 v8, v38
	v_mov_b32_e32 v9, v38
	s_mov_b64 s[12:13], 0x6000
	s_mov_b64 s[16:17], 0x30000
.LBB0_393:
	v_lshl_add_u64 v[84:85], v[48:49], 0, s[12:13]
	v_lshl_add_u64 v[86:87], v[84:85], 0, s[12:13]
	v_lshl_add_u64 v[88:89], v[86:87], 0, s[12:13]
	v_lshl_add_u64 v[90:91], v[88:89], 0, s[12:13]
	v_lshl_add_u64 v[92:93], v[90:91], 0, s[12:13]
	v_lshl_add_u64 v[94:95], v[92:93], 0, s[12:13]
	v_lshl_add_u64 v[96:97], v[94:95], 0, s[12:13]
	global_load_dwordx4 v[100:103], v[48:49], off
	global_load_dwordx4 v[104:107], v[84:85], off
	global_load_dwordx4 v[108:111], v[86:87], off
	global_load_dwordx4 v[112:115], v[88:89], off
	global_load_dwordx4 v[116:119], v[90:91], off
	global_load_dwordx4 v[120:123], v[92:93], off
	global_load_dwordx4 v[124:127], v[94:95], off
	global_load_dwordx4 v[128:131], v[96:97], off
	s_add_i32 s15, s10, 0xffff0000
	v_mov_b32_e32 v244, s15
	v_mov_b32_e32 v245, s10
	ds_read_b128 v[164:167], v244
	ds_read_b128 v[208:211], v244 offset:16
	ds_read_b128 v[168:171], v244 offset:8192
	ds_read_b128 v[212:215], v244 offset:8208
	ds_read_b128 v[172:175], v244 offset:16384
	ds_read_b128 v[216:219], v244 offset:16400
	ds_read_b128 v[176:179], v244 offset:24576
	ds_read_b128 v[220:223], v244 offset:24592
	ds_read_b128 v[180:183], v244 offset:32768
	ds_read_b128 v[224:227], v244 offset:32784
	ds_read_b128 v[192:195], v244 offset:40960
	ds_read_b128 v[228:231], v244 offset:40976
	ds_read_b128 v[196:199], v244 offset:49152
	ds_read_b128 v[232:235], v244 offset:49168
	ds_read_b128 v[200:203], v244 offset:57344
	ds_read_b128 v[236:239], v244 offset:57360
	ds_read_b128 v[204:207], v245
	ds_read_b128 v[240:243], v245 offset:16
	s_add_i32 s10, s10, 32
	s_add_i32 s11, s11, 8
	v_lshl_add_u64 v[48:49], v[48:49], 0, s[16:17]
	s_waitcnt vmcnt(0) lgkmcnt(0)
	v_pk_fma_f32 v[38:39], v[100:101], v[164:165], v[38:39] op_sel_hi:[1,0,1]
	v_pk_fma_f32 v[40:41], v[102:103], v[164:165], v[40:41] op_sel_hi:[1,0,1]
	v_pk_fma_f32 v[42:43], v[100:101], v[168:169], v[42:43] op_sel_hi:[1,0,1]
	v_pk_fma_f32 v[44:45], v[102:103], v[168:169], v[44:45] op_sel_hi:[1,0,1]
	v_pk_fma_f32 v[34:35], v[100:101], v[172:173], v[34:35] op_sel_hi:[1,0,1]
	v_pk_fma_f32 v[36:37], v[102:103], v[172:173], v[36:37] op_sel_hi:[1,0,1]
	v_pk_fma_f32 v[30:31], v[100:101], v[176:177], v[30:31] op_sel_hi:[1,0,1]
	v_pk_fma_f32 v[32:33], v[102:103], v[176:177], v[32:33] op_sel_hi:[1,0,1]
	v_pk_fma_f32 v[26:27], v[100:101], v[180:181], v[26:27] op_sel_hi:[1,0,1]
	v_pk_fma_f32 v[28:29], v[102:103], v[180:181], v[28:29] op_sel_hi:[1,0,1]
	v_pk_fma_f32 v[14:15], v[100:101], v[192:193], v[14:15] op_sel_hi:[1,0,1]
	v_pk_fma_f32 v[16:17], v[102:103], v[192:193], v[16:17] op_sel_hi:[1,0,1]
	v_pk_fma_f32 v[22:23], v[100:101], v[196:197], v[22:23] op_sel_hi:[1,0,1]
	v_pk_fma_f32 v[24:25], v[102:103], v[196:197], v[24:25] op_sel_hi:[1,0,1]
	v_pk_fma_f32 v[2:3], v[100:101], v[200:201], v[2:3] op_sel_hi:[1,0,1]
	v_pk_fma_f32 v[4:5], v[102:103], v[200:201], v[4:5] op_sel_hi:[1,0,1]
	v_pk_fma_f32 v[6:7], v[100:101], v[204:205], v[6:7] op_sel_hi:[1,0,1]
	v_pk_fma_f32 v[8:9], v[102:103], v[204:205], v[8:9] op_sel_hi:[1,0,1]
	v_pk_fma_f32 v[38:39], v[104:105], v[164:165], v[38:39] op_sel:[0,1,0]
	v_pk_fma_f32 v[40:41], v[106:107], v[164:165], v[40:41] op_sel:[0,1,0]
	v_pk_fma_f32 v[42:43], v[104:105], v[168:169], v[42:43] op_sel:[0,1,0]
	v_pk_fma_f32 v[44:45], v[106:107], v[168:169], v[44:45] op_sel:[0,1,0]
	v_pk_fma_f32 v[34:35], v[104:105], v[172:173], v[34:35] op_sel:[0,1,0]
	v_pk_fma_f32 v[36:37], v[106:107], v[172:173], v[36:37] op_sel:[0,1,0]
	v_pk_fma_f32 v[30:31], v[104:105], v[176:177], v[30:31] op_sel:[0,1,0]
	v_pk_fma_f32 v[32:33], v[106:107], v[176:177], v[32:33] op_sel:[0,1,0]
	v_pk_fma_f32 v[26:27], v[104:105], v[180:181], v[26:27] op_sel:[0,1,0]
	v_pk_fma_f32 v[28:29], v[106:107], v[180:181], v[28:29] op_sel:[0,1,0]
	v_pk_fma_f32 v[14:15], v[104:105], v[192:193], v[14:15] op_sel:[0,1,0]
	v_pk_fma_f32 v[16:17], v[106:107], v[192:193], v[16:17] op_sel:[0,1,0]
; __device__ __forceinline__ void phase_prologue(const KArgs& A, LAS unsigned char* lds, int wave, int lane) {
;     ...
;             for (int i = 0; i < 8; ++i)
; #pragma unroll
;                 for (int v = 0; v < 9; ++v) acc[v] += w[i] * sl[v * 2048 + s * KS + k0 + i];
	v_pk_fma_f32 v[22:23], v[104:105], v[196:197], v[22:23] op_sel:[0,1,0]
	v_pk_fma_f32 v[24:25], v[106:107], v[196:197], v[24:25] op_sel:[0,1,0]
	v_pk_fma_f32 v[2:3], v[104:105], v[200:201], v[2:3] op_sel:[0,1,0]
	v_pk_fma_f32 v[4:5], v[106:107], v[200:201], v[4:5] op_sel:[0,1,0]
	v_pk_fma_f32 v[6:7], v[104:105], v[204:205], v[6:7] op_sel:[0,1,0]
	v_pk_fma_f32 v[8:9], v[106:107], v[204:205], v[8:9] op_sel:[0,1,0]
	v_pk_fma_f32 v[38:39], v[108:109], v[166:167], v[38:39] op_sel_hi:[1,0,1]
	v_pk_fma_f32 v[40:41], v[110:111], v[166:167], v[40:41] op_sel_hi:[1,0,1]
	v_pk_fma_f32 v[42:43], v[108:109], v[170:171], v[42:43] op_sel_hi:[1,0,1]
	v_pk_fma_f32 v[44:45], v[110:111], v[170:171], v[44:45] op_sel_hi:[1,0,1]
	v_pk_fma_f32 v[34:35], v[108:109], v[174:175], v[34:35] op_sel_hi:[1,0,1]
	v_pk_fma_f32 v[36:37], v[110:111], v[174:175], v[36:37] op_sel_hi:[1,0,1]
	v_pk_fma_f32 v[30:31], v[108:109], v[178:179], v[30:31] op_sel_hi:[1,0,1]
	v_pk_fma_f32 v[32:33], v[110:111], v[178:179], v[32:33] op_sel_hi:[1,0,1]
	v_pk_fma_f32 v[26:27], v[108:109], v[182:183], v[26:27] op_sel_hi:[1,0,1]
	v_pk_fma_f32 v[28:29], v[110:111], v[182:183], v[28:29] op_sel_hi:[1,0,1]
	v_pk_fma_f32 v[14:15], v[108:109], v[194:195], v[14:15] op_sel_hi:[1,0,1]
	v_pk_fma_f32 v[16:17], v[110:111], v[194:195], v[16:17] op_sel_hi:[1,0,1]
	v_pk_fma_f32 v[22:23], v[108:109], v[198:199], v[22:23] op_sel_hi:[1,0,1]
	v_pk_fma_f32 v[24:25], v[110:111], v[198:199], v[24:25] op_sel_hi:[1,0,1]
	v_pk_fma_f32 v[2:3], v[108:109], v[202:203], v[2:3] op_sel_hi:[1,0,1]
	v_pk_fma_f32 v[4:5], v[110:111], v[202:203], v[4:5] op_sel_hi:[1,0,1]
	v_pk_fma_f32 v[6:7], v[108:109], v[206:207], v[6:7] op_sel_hi:[1,0,1]
	v_pk_fma_f32 v[8:9], v[110:111], v[206:207], v[8:9] op_sel_hi:[1,0,1]
	v_pk_fma_f32 v[38:39], v[112:113], v[166:167], v[38:39] op_sel:[0,1,0]
	v_pk_fma_f32 v[40:41], v[114:115], v[166:167], v[40:41] op_sel:[0,1,0]
	v_pk_fma_f32 v[42:43], v[112:113], v[170:171], v[42:43] op_sel:[0,1,0]
	v_pk_fma_f32 v[44:45], v[114:115], v[170:171], v[44:45] op_sel:[0,1,0]
	v_pk_fma_f32 v[34:35], v[112:113], v[174:175], v[34:35] op_sel:[0,1,0]
	v_pk_fma_f32 v[36:37], v[114:115], v[174:175], v[36:37] op_sel:[0,1,0]
	v_pk_fma_f32 v[30:31], v[112:113], v[178:179], v[30:31] op_sel:[0,1,0]
	v_pk_fma_f32 v[32:33], v[114:115], v[178:179], v[32:33] op_sel:[0,1,0]
	v_pk_fma_f32 v[26:27], v[112:113], v[182:183], v[26:27] op_sel:[0,1,0]
	v_pk_fma_f32 v[28:29], v[114:115], v[182:183], v[28:29] op_sel:[0,1,0]
	v_pk_fma_f32 v[14:15], v[112:113], v[194:195], v[14:15] op_sel:[0,1,0]
	v_pk_fma_f32 v[16:17], v[114:115], v[194:195], v[16:17] op_sel:[0,1,0]
	v_pk_fma_f32 v[22:23], v[112:113], v[198:199], v[22:23] op_sel:[0,1,0]
	v_pk_fma_f32 v[24:25], v[114:115], v[198:199], v[24:25] op_sel:[0,1,0]
	v_pk_fma_f32 v[2:3], v[112:113], v[202:203], v[2:3] op_sel:[0,1,0]
	v_pk_fma_f32 v[4:5], v[114:115], v[202:203], v[4:5] op_sel:[0,1,0]
	v_pk_fma_f32 v[6:7], v[112:113], v[206:207], v[6:7] op_sel:[0,1,0]
	v_pk_fma_f32 v[8:9], v[114:115], v[206:207], v[8:9] op_sel:[0,1,0]
	v_pk_fma_f32 v[38:39], v[116:117], v[208:209], v[38:39] op_sel_hi:[1,0,1]
	v_pk_fma_f32 v[40:41], v[118:119], v[208:209], v[40:41] op_sel_hi:[1,0,1]
	v_pk_fma_f32 v[42:43], v[116:117], v[212:213], v[42:43] op_sel_hi:[1,0,1]
	v_pk_fma_f32 v[44:45], v[118:119], v[212:213], v[44:45] op_sel_hi:[1,0,1]
	v_pk_fma_f32 v[34:35], v[116:117], v[216:217], v[34:35] op_sel_hi:[1,0,1]
	v_pk_fma_f32 v[36:37], v[118:119], v[216:217], v[36:37] op_sel_hi:[1,0,1]
	v_pk_fma_f32 v[30:31], v[116:117], v[220:221], v[30:31] op_sel_hi:[1,0,1]
	v_pk_fma_f32 v[32:33], v[118:119], v[220:221], v[32:33] op_sel_hi:[1,0,1]
	v_pk_fma_f32 v[26:27], v[116:117], v[224:225], v[26:27] op_sel_hi:[1,0,1]
	v_pk_fma_f32 v[28:29], v[118:119], v[224:225], v[28:29] op_sel_hi:[1,0,1]
	v_pk_fma_f32 v[14:15], v[116:117], v[228:229], v[14:15] op_sel_hi:[1,0,1]
	v_pk_fma_f32 v[16:17], v[118:119], v[228:229], v[16:17] op_sel_hi:[1,0,1]
	v_pk_fma_f32 v[22:23], v[116:117], v[232:233], v[22:23] op_sel_hi:[1,0,1]
	v_pk_fma_f32 v[24:25], v[118:119], v[232:233], v[24:25] op_sel_hi:[1,0,1]
	v_pk_fma_f32 v[2:3], v[116:117], v[236:237], v[2:3] op_sel_hi:[1,0,1]
	v_pk_fma_f32 v[4:5], v[118:119], v[236:237], v[4:5] op_sel_hi:[1,0,1]
	v_pk_fma_f32 v[6:7], v[116:117], v[240:241], v[6:7] op_sel_hi:[1,0,1]
	v_pk_fma_f32 v[8:9], v[118:119], v[240:241], v[8:9] op_sel_hi:[1,0,1]
	v_pk_fma_f32 v[38:39], v[120:121], v[208:209], v[38:39] op_sel:[0,1,0]
	v_pk_fma_f32 v[40:41], v[122:123], v[208:209], v[40:41] op_sel:[0,1,0]
	v_pk_fma_f32 v[42:43], v[120:121], v[212:213], v[42:43] op_sel:[0,1,0]
	v_pk_fma_f32 v[44:45], v[122:123], v[212:213], v[44:45] op_sel:[0,1,0]
	v_pk_fma_f32 v[34:35], v[120:121], v[216:217], v[34:35] op_sel:[0,1,0]
	v_pk_fma_f32 v[36:37], v[122:123], v[216:217], v[36:37] op_sel:[0,1,0]
	v_pk_fma_f32 v[30:31], v[120:121], v[220:221], v[30:31] op_sel:[0,1,0]
; __device__ __forceinline__ void phase_prologue(const KArgs& A, LAS unsigned char* lds, int wave, int lane) {
;     ...
;             for (int i = 0; i < 8; ++i)
; #pragma unroll
;                 for (int v = 0; v < 9; ++v) acc[v] += w[i] * sl[v * 2048 + s * KS + k0 + i];
;         }
; #pragma unroll
;         for (int v = 0; v < 9; ++v) *(f32x4*)(part + ((size_t)(s * 4 + l) * 9 + v) * 6144 + cgp * 256 + lane * 4) = acc[v];
;     }
	v_pk_fma_f32 v[32:33], v[122:123], v[220:221], v[32:33] op_sel:[0,1,0]
	v_pk_fma_f32 v[26:27], v[120:121], v[224:225], v[26:27] op_sel:[0,1,0]
	v_pk_fma_f32 v[28:29], v[122:123], v[224:225], v[28:29] op_sel:[0,1,0]
	v_pk_fma_f32 v[14:15], v[120:121], v[228:229], v[14:15] op_sel:[0,1,0]
	v_pk_fma_f32 v[16:17], v[122:123], v[228:229], v[16:17] op_sel:[0,1,0]
	v_pk_fma_f32 v[22:23], v[120:121], v[232:233], v[22:23] op_sel:[0,1,0]
	v_pk_fma_f32 v[24:25], v[122:123], v[232:233], v[24:25] op_sel:[0,1,0]
	v_pk_fma_f32 v[2:3], v[120:121], v[236:237], v[2:3] op_sel:[0,1,0]
	v_pk_fma_f32 v[4:5], v[122:123], v[236:237], v[4:5] op_sel:[0,1,0]
	v_pk_fma_f32 v[6:7], v[120:121], v[240:241], v[6:7] op_sel:[0,1,0]
	v_pk_fma_f32 v[8:9], v[122:123], v[240:241], v[8:9] op_sel:[0,1,0]
	v_pk_fma_f32 v[38:39], v[124:125], v[210:211], v[38:39] op_sel_hi:[1,0,1]
	v_pk_fma_f32 v[40:41], v[126:127], v[210:211], v[40:41] op_sel_hi:[1,0,1]
	v_pk_fma_f32 v[42:43], v[124:125], v[214:215], v[42:43] op_sel_hi:[1,0,1]
	v_pk_fma_f32 v[44:45], v[126:127], v[214:215], v[44:45] op_sel_hi:[1,0,1]
	v_pk_fma_f32 v[34:35], v[124:125], v[218:219], v[34:35] op_sel_hi:[1,0,1]
	v_pk_fma_f32 v[36:37], v[126:127], v[218:219], v[36:37] op_sel_hi:[1,0,1]
	v_pk_fma_f32 v[30:31], v[124:125], v[222:223], v[30:31] op_sel_hi:[1,0,1]
	v_pk_fma_f32 v[32:33], v[126:127], v[222:223], v[32:33] op_sel_hi:[1,0,1]
	v_pk_fma_f32 v[26:27], v[124:125], v[226:227], v[26:27] op_sel_hi:[1,0,1]
	v_pk_fma_f32 v[28:29], v[126:127], v[226:227], v[28:29] op_sel_hi:[1,0,1]
	v_pk_fma_f32 v[14:15], v[124:125], v[230:231], v[14:15] op_sel_hi:[1,0,1]
	v_pk_fma_f32 v[16:17], v[126:127], v[230:231], v[16:17] op_sel_hi:[1,0,1]
	v_pk_fma_f32 v[22:23], v[124:125], v[234:235], v[22:23] op_sel_hi:[1,0,1]
	v_pk_fma_f32 v[24:25], v[126:127], v[234:235], v[24:25] op_sel_hi:[1,0,1]
	v_pk_fma_f32 v[2:3], v[124:125], v[238:239], v[2:3] op_sel_hi:[1,0,1]
	v_pk_fma_f32 v[4:5], v[126:127], v[238:239], v[4:5] op_sel_hi:[1,0,1]
	v_pk_fma_f32 v[6:7], v[124:125], v[242:243], v[6:7] op_sel_hi:[1,0,1]
	v_pk_fma_f32 v[8:9], v[126:127], v[242:243], v[8:9] op_sel_hi:[1,0,1]
	v_pk_fma_f32 v[38:39], v[128:129], v[210:211], v[38:39] op_sel:[0,1,0]
	v_pk_fma_f32 v[40:41], v[130:131], v[210:211], v[40:41] op_sel:[0,1,0]
	v_pk_fma_f32 v[42:43], v[128:129], v[214:215], v[42:43] op_sel:[0,1,0]
	v_pk_fma_f32 v[44:45], v[130:131], v[214:215], v[44:45] op_sel:[0,1,0]
	v_pk_fma_f32 v[34:35], v[128:129], v[218:219], v[34:35] op_sel:[0,1,0]
	v_pk_fma_f32 v[36:37], v[130:131], v[218:219], v[36:37] op_sel:[0,1,0]
	v_pk_fma_f32 v[30:31], v[128:129], v[222:223], v[30:31] op_sel:[0,1,0]
	v_pk_fma_f32 v[32:33], v[130:131], v[222:223], v[32:33] op_sel:[0,1,0]
	v_pk_fma_f32 v[26:27], v[128:129], v[226:227], v[26:27] op_sel:[0,1,0]
	v_pk_fma_f32 v[28:29], v[130:131], v[226:227], v[28:29] op_sel:[0,1,0]
	v_pk_fma_f32 v[14:15], v[128:129], v[230:231], v[14:15] op_sel:[0,1,0]
	v_pk_fma_f32 v[16:17], v[130:131], v[230:231], v[16:17] op_sel:[0,1,0]
	v_pk_fma_f32 v[22:23], v[128:129], v[234:235], v[22:23] op_sel:[0,1,0]
	v_pk_fma_f32 v[24:25], v[130:131], v[234:235], v[24:25] op_sel:[0,1,0]
	v_pk_fma_f32 v[2:3], v[128:129], v[238:239], v[2:3] op_sel:[0,1,0]
	v_pk_fma_f32 v[4:5], v[130:131], v[238:239], v[4:5] op_sel:[0,1,0]
	v_pk_fma_f32 v[6:7], v[128:129], v[242:243], v[6:7] op_sel:[0,1,0]
	v_pk_fma_f32 v[8:9], v[130:131], v[242:243], v[8:9] op_sel:[0,1,0]
	s_cmpk_gt_u32 s11, 0x77
	s_cbranch_scc0 .LBB0_393
	s_lshl_b32 s9, s9, 2
	s_add_i32 s8, s9, s8
	s_mul_i32 s8, s8, 9
	v_lshl_add_u64 v[10:11], s[6:7], 2, v[46:47]
	v_mov_b32_e32 v12, 0x6000
	v_mad_i64_i32 v[10:11], s[6:7], s8, v12, v[10:11]
	v_add_co_u32_e32 v12, vcc, s64, v10
	s_add_i32 s2, s2, s74
	s_nop 0
	v_addc_co_u32_e32 v13, vcc, 0, v11, vcc
	global_store_dwordx4 v[12:13], v[42:45], off
	v_add_co_u32_e32 v12, vcc, s73, v10
	s_cmpk_gt_i32 s2, 0x5ff
	s_nop 0
	v_addc_co_u32_e32 v13, vcc, 0, v11, vcc
	global_store_dwordx4 v[12:13], v[34:37], off
	v_add_co_u32_e32 v12, vcc, s80, v10
	global_store_dwordx4 v[10:11], v[38:41], off
	s_nop 0
	v_addc_co_u32_e32 v13, vcc, 0, v11, vcc
	global_store_dwordx4 v[12:13], v[30:33], off
	v_add_co_u32_e32 v12, vcc, s84, v10
	s_nop 1
	v_addc_co_u32_e32 v13, vcc, 0, v11, vcc
	global_store_dwordx4 v[12:13], v[26:29], off
	v_add_co_u32_e32 v12, vcc, s34, v10
	s_nop 1
	v_addc_co_u32_e32 v13, vcc, 0, v11, vcc
	global_store_dwordx4 v[12:13], v[14:17], off
	v_add_co_u32_e32 v12, vcc, 0x24000, v10
	s_nop 1
	v_addc_co_u32_e32 v13, vcc, 0, v11, vcc
	global_store_dwordx4 v[12:13], v[22:25], off
	v_add_co_u32_e32 v12, vcc, 0x2a000, v10
	s_nop 1
	v_addc_co_u32_e32 v13, vcc, 0, v11, vcc
	global_store_dwordx4 v[12:13], v[2:5], off
	s_nop 1
	v_add_co_u32_e32 v2, vcc, 0x30000, v10
	s_nop 1
	v_addc_co_u32_e32 v3, vcc, 0, v11, vcc
	global_store_dwordx4 v[2:3], v[6:9], off
	s_cbranch_scc0 .LBB0_390
